# attention: the 8-score fast path also for the tile whose distances straddle 512 (STR512 class)
# speedup vs baseline: 1.0046x; 1.0028x over previous
; template <int CLS> __device__ __forceinline__ void bias_tile(f32x16& p0, f32x16& p1, int dq, float slr, int dq15, int dq3) {
;     ...
;     for (int r = 0; r < 16; ++r) {
; #pragma unroll
;         for (int hf = 0; hf < 2; ++hf) {
;             const int C = (r & 3) + 8 * (r >> 2) + 32 * hf;
;             float v = hf ? p1[r] : p0[r];
;             v = __builtin_fmaf(slr, (float)C, v);
;             const bool m16 = dq15 == (C & 15), m4 = dq3 == (C & 3);
;             if (CLS == 2) { v = m16 ? v : NEG; }
;             else if (CLS == 1) { const float v2 = v + L2R; v = m16 ? v2 : v; v = m4 ? v : NEG; }
;             else if (CLS == 3 || CLS == 4) { float bb = m4 ? L2R : 0.f; bb = m16 ? L3R : bb; v += bb; if (CLS == 4) v = (dq >= C) ? v : NEG; }
;             else if (CLS == 5) { const bool n1 = dq <= C + 128; const float b16 = n1 ? L3R : L2R, b4 = n1 ? L2R : 0.f, b1 = n1 ? 0.f : NEG; v += m16 ? b16 : (m4 ? b4 : b1); }
;             else { const bool n5 = dq <= C + 512; const float b16 = n5 ? L2R : 0.f, b4 = n5 ? 0.f : NEG; v += m16 ? b16 : (m4 ? b4 : NEG); }
;             if (hf) p1[r] = v; else p0[r] = v;
; __device__ __forceinline__ void attn_block(const bf16_t* __restrict__ proj, bf16_t* __restrict__ mixed, int b, int h, int qb, char* lds) {
;     ...
;                 if (dmin < 0) bias_tile<4>(p0, p1, dq, slr, dq15, dq3);
;                 else if (dmax <= 128) bias_tile<3>(p0, p1, dq, slr, dq15, dq3);
;                 else if (dmin <= 128) bias_tile<5>(p0, p1, dq, slr, dq15, dq3);
;                 else if (dmax <= 512) bias_tile<1>(p0, p1, dq, slr, dq15, dq3);
;                 else bias_tile<6>(p0, p1, dq, slr, dq15, dq3);
.LBB0_317:
	s_cmp_gt_i32 s65, 62
	s_cbranch_scc0 .LBB0_331
	s_add_i32 s57, s65, 31
	s_cmpk_gt_i32 s57, 0x80
	s_cbranch_scc0 .LBB0_328
	s_cmpk_gt_u32 s65, 0xbf
	s_cbranch_scc0 .LBB0_325
	s_cmpk_gt_u32 s57, 0x200
	s_cbranch_scc0 .Lmid_fast
	s_branch .Lstr512_fast
	s_movk_i32 s57, 0x200
	v_cmp_lt_i32_e32 vcc, s57, v0
	s_movk_i32 s57, 0x220
	s_mov_b64 s[96:97], 0
	v_cndmask_b32_e32 v3, 0, v187, vcc
	v_cndmask_b32_e64 v2, v182, 0, vcc
	v_cndmask_b32_e64 v3, v187, v3, s[26:27]
	v_cndmask_b32_e64 v2, v3, v2, s[28:29]
	v_fma_f32 v3, 0, v203, v96
	v_cmp_lt_i32_e32 vcc, s57, v0
	v_add_f32_e32 v112, v2, v3
	s_movk_i32 s57, 0x201
	v_cndmask_b32_e32 v3, 0, v187, vcc
	v_cndmask_b32_e64 v2, v182, 0, vcc
	v_cndmask_b32_e64 v3, v187, v3, s[26:27]
	v_cndmask_b32_e64 v2, v3, v2, s[28:29]
	v_fmamk_f32 v3, v203, 0x42000000, v80
	v_cmp_lt_i32_e32 vcc, s57, v0
	v_add_f32_e32 v128, v2, v3
	s_movk_i32 s57, 0x221
	v_cndmask_b32_e32 v3, 0, v187, vcc
	v_cndmask_b32_e64 v2, v182, 0, vcc
	v_cndmask_b32_e64 v3, v187, v3, s[30:31]
	v_cndmask_b32_e64 v2, v3, v2, s[34:35]
	v_add_f32_e32 v3, v203, v97
	v_cmp_lt_i32_e32 vcc, s57, v0
	v_add_f32_e32 v113, v2, v3
	s_movk_i32 s57, 0x202
	v_cndmask_b32_e32 v3, 0, v187, vcc
	v_cndmask_b32_e64 v2, v182, 0, vcc
	v_cndmask_b32_e64 v3, v187, v3, s[30:31]
	v_cndmask_b32_e64 v2, v3, v2, s[34:35]
	v_fmamk_f32 v3, v203, 0x42040000, v81
	v_cmp_lt_i32_e32 vcc, s57, v0
	v_add_f32_e32 v129, v2, v3
	s_movk_i32 s57, 0x222
	v_cndmask_b32_e32 v3, 0, v187, vcc
	v_cndmask_b32_e64 v2, v182, 0, vcc
	v_cndmask_b32_e64 v3, v187, v3, s[36:37]
	v_cndmask_b32_e64 v2, v3, v2, s[38:39]
	v_fma_f32 v3, 2.0, v203, v98
	v_cmp_lt_i32_e32 vcc, s57, v0
	v_add_f32_e32 v114, v2, v3
	s_movk_i32 s57, 0x203
	v_cndmask_b32_e32 v3, 0, v187, vcc
	v_cndmask_b32_e64 v2, v182, 0, vcc
	v_cndmask_b32_e64 v3, v187, v3, s[36:37]
	v_cndmask_b32_e64 v2, v3, v2, s[38:39]
	v_fmamk_f32 v3, v203, 0x42080000, v82
	v_cmp_lt_i32_e32 vcc, s57, v0
	v_add_f32_e32 v130, v2, v3
	s_movk_i32 s57, 0x223
	v_cndmask_b32_e32 v3, 0, v187, vcc
	v_cndmask_b32_e64 v2, v182, 0, vcc
	v_cndmask_b32_e64 v3, v187, v3, s[40:41]
	v_cndmask_b32_e64 v2, v3, v2, s[42:43]
	v_fmamk_f32 v3, v203, 0x40400000, v99
	v_cmp_lt_i32_e32 vcc, s57, v0
	v_add_f32_e32 v115, v2, v3
	s_movk_i32 s57, 0x208
	v_cndmask_b32_e32 v3, 0, v187, vcc
	v_cndmask_b32_e64 v2, v182, 0, vcc
	v_cndmask_b32_e64 v3, v187, v3, s[40:41]
	v_cndmask_b32_e64 v2, v3, v2, s[42:43]
	v_fmamk_f32 v3, v203, 0x420c0000, v83
	v_cmp_lt_i32_e32 vcc, s57, v0
	v_add_f32_e32 v131, v2, v3
	s_movk_i32 s57, 0x228
	v_cndmask_b32_e32 v3, 0, v187, vcc
	v_cndmask_b32_e64 v2, v182, 0, vcc
	v_cndmask_b32_e64 v3, v187, v3, s[26:27]
	v_cndmask_b32_e64 v2, v3, v2, s[44:45]
	v_fmamk_f32 v3, v203, 0x41000000, v100
	v_cmp_lt_i32_e32 vcc, s57, v0
	v_add_f32_e32 v116, v2, v3
	s_movk_i32 s57, 0x209
	v_cndmask_b32_e32 v3, 0, v187, vcc
	v_cndmask_b32_e64 v2, v182, 0, vcc
	v_cndmask_b32_e64 v3, v187, v3, s[26:27]
	v_cndmask_b32_e64 v2, v3, v2, s[44:45]
	v_fmamk_f32 v3, v203, 0x42200000, v84
	v_cmp_lt_i32_e32 vcc, s57, v0
	v_add_f32_e32 v132, v2, v3
	s_movk_i32 s57, 0x229
	v_cndmask_b32_e32 v3, 0, v187, vcc
	v_cndmask_b32_e64 v2, v182, 0, vcc
	v_cndmask_b32_e64 v3, v187, v3, s[30:31]
	v_cndmask_b32_e64 v2, v3, v2, s[46:47]
	v_fmamk_f32 v3, v203, 0x41100000, v101
	v_cmp_lt_i32_e32 vcc, s57, v0
	v_add_f32_e32 v117, v2, v3
	s_movk_i32 s57, 0x20a
	v_cndmask_b32_e32 v3, 0, v187, vcc
	v_cndmask_b32_e64 v2, v182, 0, vcc
	v_cndmask_b32_e64 v3, v187, v3, s[30:31]
	v_cndmask_b32_e64 v2, v3, v2, s[46:47]
	v_fmamk_f32 v3, v203, 0x42240000, v85
	v_cmp_lt_i32_e32 vcc, s57, v0
	v_add_f32_e32 v133, v2, v3
	s_movk_i32 s57, 0x22a
	v_cndmask_b32_e32 v3, 0, v187, vcc
	v_cndmask_b32_e64 v2, v182, 0, vcc
	v_cndmask_b32_e64 v3, v187, v3, s[36:37]
	v_cndmask_b32_e64 v2, v3, v2, s[48:49]
	v_fmamk_f32 v3, v203, 0x41200000, v102
	v_cmp_lt_i32_e32 vcc, s57, v0
	v_add_f32_e32 v118, v2, v3
	s_movk_i32 s57, 0x20b
	v_cndmask_b32_e32 v3, 0, v187, vcc
	v_cndmask_b32_e64 v2, v182, 0, vcc
	v_cndmask_b32_e64 v3, v187, v3, s[36:37]
	v_cndmask_b32_e64 v2, v3, v2, s[48:49]
	v_fmamk_f32 v3, v203, 0x42280000, v86
	v_cmp_lt_i32_e32 vcc, s57, v0
	v_add_f32_e32 v134, v2, v3
	s_movk_i32 s57, 0x22b
	v_cndmask_b32_e32 v3, 0, v187, vcc
	v_cndmask_b32_e64 v2, v182, 0, vcc
	v_cndmask_b32_e64 v3, v187, v3, s[40:41]
	v_cndmask_b32_e64 v2, v3, v2, s[50:51]
	v_fmamk_f32 v3, v203, 0x41300000, v103
	v_cmp_lt_i32_e32 vcc, s57, v0
	v_add_f32_e32 v119, v2, v3
	s_movk_i32 s57, 0x210
	v_cndmask_b32_e32 v3, 0, v187, vcc
	v_cndmask_b32_e64 v2, v182, 0, vcc
; template <int CLS> __device__ __forceinline__ void bias_tile(f32x16& p0, f32x16& p1, int dq, float slr, int dq15, int dq3) {
;     ...
;     for (int r = 0; r < 16; ++r) {
; #pragma unroll
;         for (int hf = 0; hf < 2; ++hf) {
;             const int C = (r & 3) + 8 * (r >> 2) + 32 * hf;
;             float v = hf ? p1[r] : p0[r];
;             v = __builtin_fmaf(slr, (float)C, v);
;             const bool m16 = dq15 == (C & 15), m4 = dq3 == (C & 3);
;             if (CLS == 2) { v = m16 ? v : NEG; }
;             else if (CLS == 1) { const float v2 = v + L2R; v = m16 ? v2 : v; v = m4 ? v : NEG; }
;             else if (CLS == 3 || CLS == 4) { float bb = m4 ? L2R : 0.f; bb = m16 ? L3R : bb; v += bb; if (CLS == 4) v = (dq >= C) ? v : NEG; }
;             else if (CLS == 5) { const bool n1 = dq <= C + 128; const float b16 = n1 ? L3R : L2R, b4 = n1 ? L2R : 0.f, b1 = n1 ? 0.f : NEG; v += m16 ? b16 : (m4 ? b4 : b1); }
;             else { const bool n5 = dq <= C + 512; const float b16 = n5 ? L2R : 0.f, b4 = n5 ? 0.f : NEG; v += m16 ? b16 : (m4 ? b4 : NEG); }
;             if (hf) p1[r] = v; else p0[r] = v;
	v_cndmask_b32_e64 v3, v187, v3, s[40:41]
	v_cndmask_b32_e64 v2, v3, v2, s[50:51]
	v_fmamk_f32 v3, v203, 0x422c0000, v87
	v_cmp_lt_i32_e32 vcc, s57, v0
	v_add_f32_e32 v135, v2, v3
	s_movk_i32 s57, 0x230
	v_cndmask_b32_e32 v3, 0, v187, vcc
	v_cndmask_b32_e64 v2, v182, 0, vcc
	v_cndmask_b32_e64 v3, v187, v3, s[26:27]
	v_cndmask_b32_e64 v2, v3, v2, s[28:29]
	v_fmamk_f32 v3, v203, 0x41800000, v104
	v_cmp_lt_i32_e32 vcc, s57, v0
	v_add_f32_e32 v120, v2, v3
	s_movk_i32 s57, 0x211
	v_cndmask_b32_e32 v3, 0, v187, vcc
	v_cndmask_b32_e64 v2, v182, 0, vcc
	v_cndmask_b32_e64 v3, v187, v3, s[26:27]
	v_cndmask_b32_e64 v2, v3, v2, s[28:29]
	v_fmamk_f32 v3, v203, 0x42400000, v88
	v_cmp_lt_i32_e32 vcc, s57, v0
	v_add_f32_e32 v136, v2, v3
	s_movk_i32 s57, 0x231
	v_cndmask_b32_e32 v3, 0, v187, vcc
	v_cndmask_b32_e64 v2, v182, 0, vcc
	v_cndmask_b32_e64 v3, v187, v3, s[30:31]
	v_cndmask_b32_e64 v2, v3, v2, s[34:35]
	v_fmamk_f32 v3, v203, 0x41880000, v105
	v_cmp_lt_i32_e32 vcc, s57, v0
	v_add_f32_e32 v121, v2, v3
	s_movk_i32 s57, 0x212
	v_cndmask_b32_e32 v3, 0, v187, vcc
	v_cndmask_b32_e64 v2, v182, 0, vcc
	v_cndmask_b32_e64 v3, v187, v3, s[30:31]
	v_cndmask_b32_e64 v2, v3, v2, s[34:35]
	v_fmamk_f32 v3, v203, 0x42440000, v89
	v_cmp_lt_i32_e32 vcc, s57, v0
	v_add_f32_e32 v137, v2, v3
	s_movk_i32 s57, 0x232
	v_cndmask_b32_e32 v3, 0, v187, vcc
	v_cndmask_b32_e64 v2, v182, 0, vcc
	v_cndmask_b32_e64 v3, v187, v3, s[36:37]
	v_cndmask_b32_e64 v2, v3, v2, s[38:39]
	v_fmamk_f32 v3, v203, 0x41900000, v106
	v_cmp_lt_i32_e32 vcc, s57, v0
	v_add_f32_e32 v122, v2, v3
	s_movk_i32 s57, 0x213
	v_cndmask_b32_e32 v3, 0, v187, vcc
	v_cndmask_b32_e64 v2, v182, 0, vcc
	v_cndmask_b32_e64 v3, v187, v3, s[36:37]
	v_cndmask_b32_e64 v2, v3, v2, s[38:39]
	v_fmamk_f32 v3, v203, 0x42480000, v90
	v_cmp_lt_i32_e32 vcc, s57, v0
	v_add_f32_e32 v138, v2, v3
	s_movk_i32 s57, 0x233
	v_cndmask_b32_e32 v3, 0, v187, vcc
	v_cndmask_b32_e64 v2, v182, 0, vcc
	v_cndmask_b32_e64 v3, v187, v3, s[40:41]
	v_cndmask_b32_e64 v2, v3, v2, s[42:43]
	v_fmamk_f32 v3, v203, 0x41980000, v107
	v_cmp_lt_i32_e32 vcc, s57, v0
	v_add_f32_e32 v123, v2, v3
	s_movk_i32 s57, 0x218
	v_cndmask_b32_e32 v3, 0, v187, vcc
	v_cndmask_b32_e64 v2, v182, 0, vcc
	v_cndmask_b32_e64 v3, v187, v3, s[40:41]
	v_cndmask_b32_e64 v2, v3, v2, s[42:43]
	v_fmamk_f32 v3, v203, 0x424c0000, v91
	v_cmp_lt_i32_e32 vcc, s57, v0
	v_add_f32_e32 v139, v2, v3
	s_movk_i32 s57, 0x238
	v_cndmask_b32_e32 v3, 0, v187, vcc
	v_cndmask_b32_e64 v2, v182, 0, vcc
	v_cndmask_b32_e64 v3, v187, v3, s[26:27]
	v_cndmask_b32_e64 v2, v3, v2, s[44:45]
	v_fmamk_f32 v3, v203, 0x41c00000, v108
	v_cmp_lt_i32_e32 vcc, s57, v0
	v_add_f32_e32 v124, v2, v3
	s_movk_i32 s57, 0x219
	v_cndmask_b32_e32 v3, 0, v187, vcc
	v_cndmask_b32_e64 v2, v182, 0, vcc
	v_cndmask_b32_e64 v3, v187, v3, s[26:27]
	v_cndmask_b32_e64 v2, v3, v2, s[44:45]
	v_fmamk_f32 v3, v203, 0x42600000, v92
	v_cmp_lt_i32_e32 vcc, s57, v0
	v_add_f32_e32 v140, v2, v3
	s_movk_i32 s57, 0x239
	v_cndmask_b32_e32 v3, 0, v187, vcc
	v_cndmask_b32_e64 v2, v182, 0, vcc
	v_cndmask_b32_e64 v3, v187, v3, s[30:31]
	v_cndmask_b32_e64 v2, v3, v2, s[46:47]
	v_fmamk_f32 v3, v203, 0x41c80000, v109
	v_cmp_lt_i32_e32 vcc, s57, v0
	v_add_f32_e32 v125, v2, v3
	s_movk_i32 s57, 0x21a
	v_cndmask_b32_e32 v3, 0, v187, vcc
	v_cndmask_b32_e64 v2, v182, 0, vcc
	v_cndmask_b32_e64 v3, v187, v3, s[30:31]
	v_cndmask_b32_e64 v2, v3, v2, s[46:47]
	v_fmamk_f32 v3, v203, 0x42640000, v93
	v_cmp_lt_i32_e32 vcc, s57, v0
	v_add_f32_e32 v141, v2, v3
	s_movk_i32 s57, 0x23a
	v_cndmask_b32_e32 v3, 0, v187, vcc
	v_cndmask_b32_e64 v2, v182, 0, vcc
	v_cndmask_b32_e64 v3, v187, v3, s[36:37]
	v_cndmask_b32_e64 v2, v3, v2, s[48:49]
	v_fmamk_f32 v3, v203, 0x41d00000, v110
	v_cmp_lt_i32_e32 vcc, s57, v0
	v_add_f32_e32 v126, v2, v3
	s_movk_i32 s57, 0x21b
	v_cndmask_b32_e32 v3, 0, v187, vcc
	v_cndmask_b32_e64 v2, v182, 0, vcc
	v_cndmask_b32_e64 v3, v187, v3, s[36:37]
	v_cndmask_b32_e64 v2, v3, v2, s[48:49]
	v_fmamk_f32 v3, v203, 0x42680000, v94
	v_cmp_lt_i32_e32 vcc, s57, v0
	v_add_f32_e32 v142, v2, v3
	s_movk_i32 s57, 0x23b
	v_cndmask_b32_e32 v3, 0, v187, vcc
	v_cndmask_b32_e64 v2, v182, 0, vcc
	v_cndmask_b32_e64 v3, v187, v3, s[40:41]
	v_cndmask_b32_e64 v2, v3, v2, s[50:51]
	v_fmamk_f32 v3, v203, 0x41d80000, v111
	v_cmp_lt_i32_e32 vcc, s57, v0
	v_add_f32_e32 v127, v2, v3
	s_nop 0
	v_cndmask_b32_e32 v3, 0, v187, vcc
	v_cndmask_b32_e64 v2, v182, 0, vcc
	v_cndmask_b32_e64 v3, v187, v3, s[40:41]
	v_cndmask_b32_e64 v2, v3, v2, s[50:51]
	v_fmamk_f32 v3, v203, 0x426c0000, v95
	v_add_f32_e32 v143, v2, v3

; template <int CLS> __device__ __forceinline__ void bias_tile(f32x16& p0, f32x16& p1, int dq, float slr, int dq15, int dq3) {
;     ...
;             else { const bool n5 = dq <= C + 512; const float b16 = n5 ? L2R : 0.f, b4 = n5 ? 0.f : NEG; v += m16 ? b16 : (m4 ? b4 : NEG); }
; __device__ __forceinline__ void attn_block(const bf16_t* __restrict__ proj, bf16_t* __restrict__ mixed, int b, int h, int qb, char* lds) {
;     ...
;                 const float NEG = -__builtin_inff();
;                 float e0 = FA_SEL8(p0, 0) + fc0, e1 = FA_SEL8(p0, 8) + (fc0 + 16.f * slr), e2 = FA_SEL8(p1, 0) + (fc0 + 32.f * slr), e3 = FA_SEL8(p1, 8) + (fc0 + 48.f * slr);
;     ...
;                 e0 = lane_valid ? e0 : NEG; e1 = lane_valid ? e1 : NEG; e2 = lane_valid ? e2 : NEG; e3 = lane_valid ? e3 : NEG;
;                 float pmax = fmaxf(fmaxf(e0, e1), fmaxf(e2, e3));
;                 { auto rr = __builtin_amdgcn_permlane32_swap(__float_as_uint(pmax), __float_as_uint(pmax), false, false); pmax = fmaxf(__uint_as_float(rr[0]), __uint_as_float(rr[1])); }
;                 constexpr float C2 = LOG2E * SCALE; float mn;
;                 if (__builtin_expect(__all((pmax - m_reg) * SCALE <= THR), 1)) { mn = m_reg; alpha = 1.f; }
;                 else { mn = fmaxf(m_reg, pmax); alpha = __builtin_amdgcn_exp2f((m_reg - mn) * C2); m_reg = mn; }
;                 const float mnL = -mn * C2;
;                 e0 = __builtin_amdgcn_exp2f(__builtin_fmaf(e0, C2, mnL)); e1 = __builtin_amdgcn_exp2f(__builtin_fmaf(e1, C2, mnL));
;                 e2 = __builtin_amdgcn_exp2f(__builtin_fmaf(e2, C2, mnL)); e3 = __builtin_amdgcn_exp2f(__builtin_fmaf(e3, C2, mnL));
;                 float ps = (e0 + e1) + (e2 + e3);
;                 { auto rr = __builtin_amdgcn_permlane32_swap(__float_as_uint(ps), __float_as_uint(ps), false, false); ps = __uint_as_float(rr[0]) + __uint_as_float(rr[1]); }
;                 l_reg = l_reg * alpha + ps;
;     ...
;                 FA_SCAT(e0, pa0); FA_SCAT(e1, pa1); FA_SCAT(e2, pa2); FA_SCAT(e3, pa3);
.Lstr512_fast:
	s_nop 3
	v_and_b32_e32 v132, 3, v0
	v_and_b32_e32 v134, 12, v0
	v_cvt_f32_u32_e32 v133, v132
	v_cmp_eq_u32_e32 vcc, 1, v132
	v_cndmask_b32_e32 v116, v96, v97, vcc
	v_cndmask_b32_e32 v117, v100, v101, vcc
	v_cndmask_b32_e32 v118, v104, v105, vcc
	v_cndmask_b32_e32 v119, v108, v109, vcc
	v_cndmask_b32_e32 v120, v80, v81, vcc
	v_cndmask_b32_e32 v121, v84, v85, vcc
	v_cndmask_b32_e32 v122, v88, v89, vcc
	v_cndmask_b32_e32 v123, v92, v93, vcc
	v_cmp_eq_u32_e32 vcc, 2, v132
	v_cndmask_b32_e32 v116, v116, v98, vcc
	v_cndmask_b32_e32 v117, v117, v102, vcc
	v_cndmask_b32_e32 v118, v118, v106, vcc
	v_cndmask_b32_e32 v119, v119, v110, vcc
	v_cndmask_b32_e32 v120, v120, v82, vcc
	v_cndmask_b32_e32 v121, v121, v86, vcc
	v_cndmask_b32_e32 v122, v122, v90, vcc
	v_cndmask_b32_e32 v123, v123, v94, vcc
	v_cmp_eq_u32_e32 vcc, 3, v132
	v_cndmask_b32_e32 v116, v116, v99, vcc
	v_cndmask_b32_e32 v117, v117, v103, vcc
	v_cndmask_b32_e32 v118, v118, v107, vcc
	v_cndmask_b32_e32 v119, v119, v111, vcc
	v_cndmask_b32_e32 v120, v120, v83, vcc
	v_cndmask_b32_e32 v121, v121, v87, vcc
	v_cndmask_b32_e32 v122, v122, v91, vcc
	v_cndmask_b32_e32 v123, v123, v95, vcc
	v_add_f32_e32 v125, 0x41000000, v133
	v_add_f32_e32 v126, 0x41800000, v133
	v_add_f32_e32 v127, 0x41c00000, v133
	v_add_f32_e32 v128, 0x42000000, v133
	v_add_f32_e32 v129, 0x42200000, v133
	v_add_f32_e32 v130, 0x42400000, v133
	v_add_f32_e32 v131, 0x42600000, v133
	v_fma_f32 v116, v203, v133, v116
	v_fma_f32 v117, v203, v125, v117
	v_fma_f32 v118, v203, v126, v118
	v_fma_f32 v119, v203, v127, v119
	v_fma_f32 v120, v203, v128, v120
	v_fma_f32 v121, v203, v129, v121
	v_fma_f32 v122, v203, v130, v122
	v_fma_f32 v123, v203, v131, v123
	v_sub_u32_e32 v139, v0, v132
	v_mov_b32_e32 v140, 0x40faf233
	v_cmp_eq_u32_e64 s[96:97], 0, v134
	s_nop 1
	v_cmp_ge_i32_e32 vcc, 0x200, v139
	v_cndmask_b32_e32 v141, 0, v140, vcc
	v_cndmask_b32_e64 v142, v187, 0, vcc
	v_cndmask_b32_e64 v141, v142, v141, s[96:97]
	v_add_f32_e32 v116, v116, v141
	v_cmp_ge_i32_e32 vcc, 0x210, v139
	v_cndmask_b32_e32 v141, 0, v140, vcc
	v_cndmask_b32_e64 v142, v187, 0, vcc
	v_cndmask_b32_e64 v141, v142, v141, s[96:97]
	v_add_f32_e32 v118, v118, v141
	v_cmp_ge_i32_e32 vcc, 0x220, v139
	v_cndmask_b32_e32 v141, 0, v140, vcc
	v_cndmask_b32_e64 v142, v187, 0, vcc
	v_cndmask_b32_e64 v141, v142, v141, s[96:97]
	v_add_f32_e32 v120, v120, v141
	v_cmp_ge_i32_e32 vcc, 0x230, v139
	v_cndmask_b32_e32 v141, 0, v140, vcc
	v_cndmask_b32_e64 v142, v187, 0, vcc
	v_cndmask_b32_e64 v141, v142, v141, s[96:97]
	v_add_f32_e32 v122, v122, v141
	v_cmp_eq_u32_e64 s[96:97], 8, v134
	s_nop 1
	v_cmp_ge_i32_e32 vcc, 0x208, v139
	v_cndmask_b32_e32 v141, 0, v140, vcc
	v_cndmask_b32_e64 v142, v187, 0, vcc
	v_cndmask_b32_e64 v141, v142, v141, s[96:97]
	v_add_f32_e32 v117, v117, v141
	v_cmp_ge_i32_e32 vcc, 0x218, v139
	v_cndmask_b32_e32 v141, 0, v140, vcc
	v_cndmask_b32_e64 v142, v187, 0, vcc
	v_cndmask_b32_e64 v141, v142, v141, s[96:97]
	v_add_f32_e32 v119, v119, v141
	v_cmp_ge_i32_e32 vcc, 0x228, v139
	v_cndmask_b32_e32 v141, 0, v140, vcc
	v_cndmask_b32_e64 v142, v187, 0, vcc
	v_cndmask_b32_e64 v141, v142, v141, s[96:97]
	v_add_f32_e32 v121, v121, v141
	v_cmp_ge_i32_e32 vcc, 0x238, v139
	v_cndmask_b32_e32 v141, 0, v140, vcc
	v_cndmask_b32_e64 v142, v187, 0, vcc
	v_cndmask_b32_e64 v141, v142, v141, s[96:97]
	v_add_f32_e32 v123, v123, v141
	v_max3_f32 v0, v116, v117, v118
	v_max3_f32 v0, v0, v119, v120
	v_max3_f32 v0, v0, v121, v122
	v_max_f32_e32 v0, v0, v123
	v_mov_b32_e32 v2, v0
	s_nop 1
	v_permlane32_swap_b32_e32 v0, v2
	v_max_f32_e32 v2, v2, v2
	v_max_f32_e32 v0, v0, v0
	v_max_f32_e32 v0, v0, v2
	v_sub_f32_e32 v2, v0, v234
	v_mul_f32_e32 v2, 0x3db504f3, v2
	v_cmp_ge_f32_e32 vcc, s58, v2
	v_max_f32_e32 v2, v234, v234
	v_max_f32_e32 v0, v2, v0
	v_sub_f32_e32 v2, v234, v0
	v_mul_f32_e32 v2, 0x3e0293ee, v2
	v_exp_f32_e32 v2, v2
	s_cmp_eq_u64 vcc, exec
	s_cselect_b64 vcc, -1, 0
	v_cndmask_b32_e32 v14, v0, v234, vcc
	v_mul_f32_e32 v0, 0xbe0293ee, v14
	v_cndmask_b32_e64 v235, v2, 1.0, vcc
	v_fmamk_f32 v116, v116, 0x3e0293ee, v0
	v_fmamk_f32 v117, v117, 0x3e0293ee, v0
	v_fmamk_f32 v118, v118, 0x3e0293ee, v0
	v_fmamk_f32 v119, v119, 0x3e0293ee, v0
	v_fmamk_f32 v120, v120, 0x3e0293ee, v0
	v_fmamk_f32 v121, v121, 0x3e0293ee, v0
	v_fmamk_f32 v122, v122, 0x3e0293ee, v0
	v_fmamk_f32 v123, v123, 0x3e0293ee, v0
	v_exp_f32_e32 v116, v116
	v_exp_f32_e32 v117, v117
	v_exp_f32_e32 v118, v118
	v_exp_f32_e32 v119, v119
	v_exp_f32_e32 v120, v120
	v_exp_f32_e32 v121, v121
	v_exp_f32_e32 v122, v122
	v_exp_f32_e32 v123, v123
	v_and_b32_e32 v135, 1, v132
	v_lshlrev_b32_e32 v135, 4, v135
	v_add_f32_e32 v15, v116, v117
	v_add_f32_e32 v15, v118, v15
	v_add_f32_e32 v15, v119, v15
	v_add_f32_e32 v15, v120, v15
	v_add_f32_e32 v15, v121, v15
	v_add_f32_e32 v15, v122, v15
	v_add_f32_e32 v15, v123, v15
	v_mov_b32_e32 v0, v15
	s_nop 1
	v_permlane32_swap_b32_e32 v15, v0
	v_add_f32_e32 v15, v15, v0
	v_fmac_f32_e32 v15, v233, v235
	v_cmp_gt_u32_e32 vcc, 2, v132
	v_cvt_pk_bf16_f32 v136, v116, 0
	v_cvt_pk_bf16_f32 v137, v117, 0
	v_lshlrev_b32_e32 v136, v135, v136
	v_lshlrev_b32_e32 v137, v135, v137
	v_cndmask_b32_e32 v2, 0, v136, vcc
	v_cndmask_b32_e64 v3, v136, 0, vcc
	v_cndmask_b32_e32 v4, 0, v137, vcc
	v_cndmask_b32_e64 v5, v137, 0, vcc
	v_cvt_pk_bf16_f32 v136, v118, 0
	v_cvt_pk_bf16_f32 v137, v119, 0
	v_lshlrev_b32_e32 v136, v135, v136
	v_lshlrev_b32_e32 v137, v135, v137
	v_cndmask_b32_e32 v6, 0, v136, vcc
	v_cndmask_b32_e64 v7, v136, 0, vcc
	v_cndmask_b32_e32 v8, 0, v137, vcc
	v_cndmask_b32_e64 v9, v137, 0, vcc
	v_cvt_pk_bf16_f32 v136, v120, 0
	v_cvt_pk_bf16_f32 v137, v121, 0
	v_lshlrev_b32_e32 v136, v135, v136
	v_lshlrev_b32_e32 v137, v135, v137
	v_cndmask_b32_e32 v10, 0, v136, vcc
	v_cndmask_b32_e64 v11, v136, 0, vcc
	v_cndmask_b32_e32 v12, 0, v137, vcc
	v_cndmask_b32_e64 v13, v137, 0, vcc
	v_cvt_pk_bf16_f32 v136, v122, 0
	v_cvt_pk_bf16_f32 v137, v123, 0
	v_lshlrev_b32_e32 v136, v135, v136
	v_lshlrev_b32_e32 v137, v135, v137
	v_cndmask_b32_e32 v112, 0, v136, vcc
	v_cndmask_b32_e64 v113, v136, 0, vcc
	v_cndmask_b32_e32 v114, 0, v137, vcc
	v_cndmask_b32_e64 v115, v137, 0, vcc
	s_nop 1
	v_permlane32_swap_b32_e32 v2, v4
	v_permlane32_swap_b32_e32 v3, v5
	v_permlane32_swap_b32_e32 v6, v8
	v_permlane32_swap_b32_e32 v7, v9
	v_permlane32_swap_b32_e32 v10, v12
	v_permlane32_swap_b32_e32 v11, v13
	v_permlane32_swap_b32_e32 v112, v114
	v_permlane32_swap_b32_e32 v113, v115
	s_branch .LBB0_315
